# attention V tile kept row-major in LDS: one ds_write_b128 per thread, PV fragments via ds_read_b64_tr_b16 from one base register
# speedup vs baseline: 1.0203x; 1.0015x over previous
; #define LAS __attribute__((address_space(3)))
; #define OPQV(x) asm volatile("" : "+v"(x))
; DEV void kv_store(LAS unsigned char* lds, const KVRegs& r, int buf, int tid) {
;     const int key = tid >> 3, c8 = (tid & 7) * 8;
;     unsigned kw = AT_KS + buf * 9216 + (key * 72 + c8) * 2, vw = AT_VT + buf * 9216 + ((tid >> 6) * 8 * 72 + (tid & 63)) * 2; OPQV(kw); OPQV(vw);
;     *(LAS u32x4*)(lds + kw) = r.k;
; #pragma unroll
;     for (int j = 0; j < 4; ++j) { *(LAS bf16_t*)(lds + vw + j * 288) = (bf16_t)(r.v[j] & 0xffffu); *(LAS bf16_t*)(lds + vw + j * 288 + 144) = (bf16_t)(r.v[j] >> 16); }
; }
; DEV void attn_item(LAS unsigned char* lds, const bf16_t* P, const bf16_t* QB, const bf16_t* KV, const bf16_t* KC, const bf16_t* VC, const float* rel_bias, bf16_t* OB, int b, int g, int qt) {
;     ...
;         for (int it = 0; it < 4; ++it) { const int q = wave * 8 + it * 2 + (lane >> 5), j = lane & 31;
;             const float v = IMPF[q * 32 + j]; int rank = 0;
;             for (int jp = 1; jp <= cur - 2; ++jp) { const float vp = IMPF[q * 32 + jp]; rank += (vp > v || (vp == v && jp < j)) ? 1 : 0; }
;             const bool sel = (j >= 1) && (j <= cur - 2) && (rank < need);
;             const unsigned long long bal = __ballot(sel);
;             const unsigned mq = forced | (unsigned)(lane < 32 ? bal : (bal >> 32));
;             if (j == 0) MASK[q] = mq; }
;     }
;     __syncthreads();
;     const unsigned mymask = MASK[qs * 16 + fr];
;     unsigned anym = MASK[lane];
; #pragma unroll
;     for (int o = 32; o >= 1; o >>= 1) anym |= __shfl_xor(anym, o);
;     anym = __builtin_amdgcn_readfirstlane(anym);
;     {
;         float cbias[2]; cbias[0] = *(const LAS float*)(lds + btb + 512); cbias[1] = *(const LAS float*)(lds + btb + 512 + 516);
;         float mrun[2] = {NEG_, NEG_}, lrun[2] = {0.f, 0.f}; f32x4 O[2][4];
; #pragma unroll
;         for (int hh = 0; hh < 2; ++hh)
; #pragma unroll
;             for (int dt = 0; dt < 4; ++dt) O[hh][dt] = (f32x4){0.f, 0.f, 0.f, 0.f};
;         unsigned rem = anym & (qt >= 31 ? 0xffffffffu : ((2u << qt) - 1u)); rem &= ~1u;
;         int mode = 1, j = 0, buf = 0;
;         for (;;) {
;             kv_store(lds, pre, buf, tid);
;             __syncthreads();
.Lrk_done:
	s_lshr_b32 s4, 0x80000000, s17
	s_lshl_b32 s5, 1, s64
	s_cmp_lg_u32 s17, 31
	s_cselect_b32 s5, s5, 0
	s_or_b32 s4, s4, s5
	s_or_b32 s92, s4, 1
	s_bcnt1_i32_b32 s4, s92
	s_sub_i32 s93, 8, s4
	v_cmp_ne_u32_e32 vcc, 0, v60
	v_cmp_ge_i32_e64 s[44:45], s36, v60
	v_and_b32_e32 v67, 32, v150
	v_lshl_add_u32 v68, v66, 2, 0
	s_and_b64 s[4:5], vcc, s[44:45]
	v_add_u32_e32 v68, 0x11c00, v68
	v_cmp_eq_u32_e64 s[42:43], 0, v60
	v_cmp_gt_i32_e32 vcc, s93, v74
	s_and_b64 vcc, s[4:5], vcc
	s_nop 0
	v_lshrrev_b64 v[78:79], v67, vcc
	v_or_b32_e32 v78, s92, v78
	v_cmp_gt_i32_e32 vcc, s93, v75
	s_and_b64 vcc, s[4:5], vcc
	s_nop 0
	v_lshrrev_b64 v[80:81], v67, vcc
	v_or_b32_e32 v80, s92, v80
	v_cmp_gt_i32_e32 vcc, s93, v76
	s_and_b64 vcc, s[4:5], vcc
	s_nop 0
	v_lshrrev_b64 v[82:83], v67, vcc
	v_or_b32_e32 v82, s92, v82
	v_cmp_gt_i32_e32 vcc, s93, v77
	s_and_b64 vcc, s[4:5], vcc
	s_nop 0
	v_lshrrev_b64 v[84:85], v67, vcc
	v_or_b32_e32 v84, s92, v84
	s_and_saveexec_b64 s[4:5], s[42:43]
	ds_write_b32 v68, v78
	ds_write_b32 v68, v80 offset:8
	ds_write_b32 v68, v82 offset:16
	ds_write_b32 v68, v84 offset:24
	s_or_b64 exec, exec, s[4:5]
	s_add_i32 s4, 0, 0x11c00
	v_lshl_add_u32 v7, v152, 2, s4
	s_waitcnt lgkmcnt(0)
	s_barrier
	ds_read_b32 v7, v7
	v_lshlrev_b32_e32 v60, 2, v137
	v_lshlrev_b32_e32 v61, 2, v136
	v_add3_u32 v60, s4, v60, v61
	ds_read_b32 v127, v60
	s_waitcnt lgkmcnt(1)
	ds_bpermute_b32 v61, v144, v7
	v_and_b32_e32 v60, 0xffff0000, v149
	v_lshlrev_b32_e32 v126, 16, v149
	s_lshl_b32 s5, 2, s15
	s_waitcnt lgkmcnt(1)
	v_pk_fma_f32 v[134:135], v[126:127], v[2:3], 0 op_sel_hi:[0,1,0]
	s_waitcnt lgkmcnt(0)
	v_or_b32_e32 v7, v61, v7
	v_pk_fma_f32 v[116:117], v[60:61], v[44:45], 0 op_sel_hi:[0,1,0]
	ds_bpermute_b32 v44, v143, v7
	v_xor_b32_e32 v3, 4, v213
	v_pk_fma_f32 v[130:131], v[126:127], v[4:5], 0 op_sel_hi:[0,1,0]
	v_pk_fma_f32 v[132:133], v[126:127], v[32:33], 0 op_sel_hi:[0,1,0]
	s_add_i32 s5, s5, -1
	s_waitcnt lgkmcnt(0)
	v_or_b32_e32 v7, v44, v7
	v_xor_b32_e32 v44, 8, v213
	v_cmp_lt_i32_e32 vcc, v44, v153
	s_and_b32 s5, s5, -2
	s_cmp_lt_u32 s15, 31
	v_cndmask_b32_e32 v44, v213, v44, vcc
	v_lshlrev_b32_e32 v44, 2, v44
	ds_bpermute_b32 v44, v44, v7
	v_cmp_lt_i32_e32 vcc, v3, v153
	s_cselect_b32 s5, s5, -2
	v_pk_fma_f32 v[114:115], v[60:61], v[46:47], 0 op_sel_hi:[0,1,0]
	v_cndmask_b32_e32 v3, v213, v3, vcc
	s_waitcnt lgkmcnt(0)
	v_or_b32_e32 v2, v44, v7
	v_lshlrev_b32_e32 v3, 2, v3
	ds_bpermute_b32 v3, v3, v2
	v_pk_fma_f32 v[110:111], v[60:61], v[50:51], 0 op_sel_hi:[0,1,0]
	v_pk_fma_f32 v[112:113], v[60:61], v[48:49], 0 op_sel_hi:[0,1,0]
	v_pk_fma_f32 v[104:105], v[60:61], v[54:55], 0 op_sel_hi:[0,1,0]
	v_pk_fma_f32 v[108:109], v[60:61], v[52:53], 0 op_sel_hi:[0,1,0]
	s_waitcnt lgkmcnt(0)
	v_or_b32_e32 v4, v3, v2
	v_xor_b32_e32 v2, 2, v213
	v_cmp_lt_i32_e32 vcc, v2, v153
	v_and_b32_e32 v3, 0xffff0000, v148
	v_pk_fma_f32 v[102:103], v[60:61], v[58:59], 0 op_sel_hi:[0,1,0]
	v_cndmask_b32_e32 v2, v213, v2, vcc
	v_lshlrev_b32_e32 v2, 2, v2
	ds_bpermute_b32 v5, v2, v4
	v_lshlrev_b32_e32 v2, 16, v148
	v_mov_b32_e32 v148, 0
	v_pk_fma_f32 v[106:107], v[60:61], v[56:57], 0 op_sel_hi:[0,1,0]
	v_pk_fma_f32 v[128:129], v[126:127], v[34:35], 0 op_sel_hi:[0,1,0]
	s_waitcnt lgkmcnt(0)
	v_or_b32_e32 v32, v5, v4
	v_xor_b32_e32 v4, 1, v213
	v_cmp_lt_i32_e32 vcc, v4, v153
	v_pk_fma_f32 v[120:121], v[126:127], v[38:39], 0 op_sel_hi:[0,1,0]
	v_pk_fma_f32 v[124:125], v[126:127], v[36:37], 0 op_sel_hi:[0,1,0]
	v_cndmask_b32_e32 v4, v213, v4, vcc
	v_lshlrev_b32_e32 v4, 2, v4
	ds_bpermute_b32 v33, v4, v32
	v_pk_fma_f32 v[118:119], v[126:127], v[42:43], 0 op_sel_hi:[0,1,0]
	v_pk_fma_f32 v[122:123], v[126:127], v[40:41], 0 op_sel_hi:[0,1,0]
	v_and_b32_e32 v5, 0xffff0000, v147
	v_lshlrev_b32_e32 v4, 16, v147
	s_waitcnt lgkmcnt(0)
	v_or_b32_e32 v32, v33, v32
	v_add_u32_e32 v33, 0x200, v142
	ds_read2_b32 v[136:137], v33 offset1:129
	v_readfirstlane_b32 s4, v32
	v_mul_lo_u32 v32, v100, s24
	v_or_b32_e32 v32, v32, v152
	v_lshl_add_u32 v146, v32, 1, v221
	v_sub_u32_e64 v32, s15, 8 clamp
	v_mov_b32_e32 v7, v60
	s_mov_b32 s97, 1
	s_and_b32 s95, s4, s5
	v_readfirstlane_b32 s94, v32
	s_sub_i32 s17, 23, s17
	v_add_u32_e32 v145, 0, v145
	s_mov_b32 s50, 0
	v_mov_b32_e32 v150, 0xf149f2ca
	v_mov_b32_e32 v147, 0
	v_mov_b32_e32 v149, 0xf149f2ca
	v_mov_b32_e32 v151, 0
	v_mov_b32_e32 v48, 0
	v_mov_b32_e32 v49, v148
	v_mov_b32_e32 v50, v148
	v_mov_b32_e32 v51, v148
	v_mov_b32_e32 v36, 0
	v_mov_b32_e32 v37, v148
	v_mov_b32_e32 v38, v148
	v_mov_b32_e32 v39, v148
	v_mov_b32_e32 v40, 0
	v_mov_b32_e32 v41, v148
	v_mov_b32_e32 v42, v148
	v_mov_b32_e32 v43, v148
	v_mov_b32_e32 v32, 0
	v_mov_b32_e32 v33, v148
	v_mov_b32_e32 v34, v148
	v_mov_b32_e32 v35, v148
	v_mov_b32_e32 v60, 0
	v_mov_b32_e32 v61, v148
	v_mov_b32_e32 v62, v148
	v_mov_b32_e32 v63, v148
	v_mov_b32_e32 v52, 0
	v_mov_b32_e32 v53, v148
	v_mov_b32_e32 v54, v148
	v_mov_b32_e32 v55, v148
	v_mov_b32_e32 v56, 0
	v_mov_b32_e32 v57, v148
	v_mov_b32_e32 v58, v148
	v_mov_b32_e32 v59, v148
	v_mov_b32_e32 v44, 0
	v_mov_b32_e32 v45, v148
	v_mov_b32_e32 v46, v148
	v_mov_b32_e32 v47, v148
	v_lshlrev_b32_e32 v192, 1, v98
	v_lshl_add_u32 v193, v100, 1, v0
	v_and_b32_e32 v194, 63, v210
	v_lshrrev_b32_e32 v195, 6, v210
	v_mul_u32_u24_e32 v194, 0x90, v194
	v_lshl_add_u32 v194, v195, 4, v194
	v_add_u32_e32 v194, 0x4800, v194
	v_and_b32_e32 v196, 15, v210
	v_bfe_u32 v197, v210, 4, 2
	v_lshrrev_b32_e32 v195, 2, v196
	v_lshl_add_u32 v195, v197, 2, v195
	v_mul_u32_u24_e32 v195, 0x90, v195
	v_and_b32_e32 v196, 3, v196
	v_lshl_add_u32 v195, v196, 3, v195
	v_add_u32_e32 v195, 0x4800, v195
	v_readfirstlane_b32 s100, v210
	s_mov_b32 s98, 0
	s_waitcnt vmcnt(1)
	ds_write_b128 v139, v[24:27]
	s_waitcnt vmcnt(0)
	ds_write_b128 v194, v[28:31]
	s_lshr_b32 s100, s100, 8
	s_mul_i32 s100, s100, 3
	s_waitcnt lgkmcnt(0)
	s_barrier

; #define LAS __attribute__((address_space(3)))
; DEV void attn_tile(LAS unsigned char* lds, const bf16x8 (&qf)[2][2], int tl, int kpos0, int mode, bool near, bool rowsel, const float (&cbias)[2],
;                    unsigned kb, unsigned vb_, unsigned btb, int g4, float (&mrun)[2], float (&lrun)[2], f32x4 (&O)[2][4]) {
;     ...
;     for (int hh = 0; hh < 2; ++hh) { const float mne = mrun[hh] < -1e29f ? 0.f : mrun[hh];
;         ci[hh] = near ? -mne : (((mode == 1 && !rowsel) ? NEG_ : cbias[hh]) - mne); }
;     {
;         bf16x8 kf[4][2];
; #pragma unroll
;         for (int kt = 0; kt < 4; ++kt) { kf[kt][0] = *(const LAS bf16x8*)(lds + kb + kt * 2304); kf[kt][1] = *(const LAS bf16x8*)(lds + kb + kt * 2304 + 64); }
;         __builtin_amdgcn_sched_barrier(0);
; #pragma unroll
;         for (int kt = 0; kt < 4; ++kt)
; #pragma unroll
;             for (int hh = 0; hh < 2; ++hh) sc[hh][kt] = __builtin_amdgcn_mfma_f32_16x16x32_bf16(kf[kt][0], qf[hh][0], (f32x4){ci[hh], ci[hh], ci[hh], ci[hh]}, 0, 0, 0);
; #pragma unroll
;         for (int kt = 0; kt < 4; ++kt)
; #pragma unroll
;             for (int hh = 0; hh < 2; ++hh) sc[hh][kt] = __builtin_amdgcn_mfma_f32_16x16x32_bf16(kf[kt][1], qf[hh][1], sc[hh][kt], 0, 0, 0);
;     }
;     ...
;     for (int dt = 0; dt < 4; ++dt)
; #pragma unroll
;         for (int kc = 0; kc < 2; ++kc) {
;             const u32x2 va = *(const LAS u32x2*)(lds + vb_ + dt * 2304 + kc * 64);
;             const u32x2 vb = *(const LAS u32x2*)(lds + vb_ + dt * 2304 + kc * 64 + 32);
;             const bf16x8 vf = as_bf16x8((u32x4){va.x, va.y, vb.x, vb.y});
; #pragma unroll
;             for (int hh = 0; hh < 2; ++hh) O[hh][dt] = __builtin_amdgcn_mfma_f32_16x16x32_bf16(vf, pf[hh][kc], O[hh][dt], 0, 0, 0);
;         }
.Lst_xx:
	s_mov_b32 s101, s99
	s_cmp_ge_i32 s50, s36
	s_cselect_b64 s[4:5], -1, 0
	s_cmp_eq_u32 s97, 2
	s_cselect_b64 s[6:7], -1, 0
	s_cmp_eq_u32 s50, s17
	s_cselect_b64 s[42:43], -1, 0
	s_and_b64 s[6:7], s[6:7], s[42:43]
	s_or_b64 s[4:5], s[4:5], s[6:7]
	v_lshrrev_b32_e32 v64, s50, v127
	v_and_b32_e32 v64, 1, v64
	s_cmp_lg_u32 s97, 1
	v_cmp_eq_u32_e64 s[48:49], 1, v64
	s_cselect_b64 s[6:7], -1, 0
	s_or_b64 vcc, s[6:7], s[48:49]
	v_cmp_gt_f32_e64 s[44:45], s65, v149
	v_cndmask_b32_e32 v65, v223, v136, vcc
	v_cmp_gt_f32_e64 s[42:43], s65, v150
	v_cndmask_b32_e64 v64, v149, 0, s[44:45]
	v_sub_f32_e32 v65, v65, v64
	v_cndmask_b32_e64 v64, v65, -v64, s[4:5]
	v_cndmask_b32_e64 v65, v150, 0, s[42:43]
	v_cndmask_b32_e32 v66, v223, v137, vcc
	v_sub_f32_e32 v66, v66, v65
	v_cndmask_b32_e64 v68, v66, -v65, s[4:5]
	v_mov_b32_e32 v65, v64
	v_mov_b32_e32 v66, v64
	v_mov_b32_e32 v67, v64
	v_mov_b32_e32 v69, v68
	v_mov_b32_e32 v70, v68
	v_mov_b32_e32 v71, v68
	s_waitcnt lgkmcnt(7)
	v_mfma_f32_16x16x32_bf16 v[162:165], v[72:75], v[8:11], v[64:67]
	s_mov_b64 s[6:7], -1
	s_and_b64 vcc, exec, s[4:5]
	v_mfma_f32_16x16x32_bf16 v[72:75], v[72:75], v[16:19], v[68:71]
	v_add_u32_e32 v228, s98, v195
	ds_read_b64_tr_b16 v[232:233], v228
	ds_read_b64_tr_b16 v[234:235], v228 offset:2304
	ds_read_b64_tr_b16 v[236:237], v228 offset:4608
	ds_read_b64_tr_b16 v[238:239], v228 offset:6912
	ds_read_b64_tr_b16 v[240:241], v228 offset:32
	ds_read_b64_tr_b16 v[242:243], v228 offset:2336
	ds_read_b64_tr_b16 v[244:245], v228 offset:4640
	ds_read_b64_tr_b16 v[246:247], v228 offset:6944
	s_waitcnt lgkmcnt(13)
	v_mfma_f32_16x16x32_bf16 v[166:169], v[80:83], v[8:11], v[64:67]
	v_mfma_f32_16x16x32_bf16 v[80:83], v[80:83], v[16:19], v[68:71]
	s_waitcnt lgkmcnt(11)
	v_mfma_f32_16x16x32_bf16 v[180:183], v[88:91], v[8:11], v[64:67]
	v_mfma_f32_16x16x32_bf16 v[184:187], v[88:91], v[16:19], v[68:71]
	s_waitcnt lgkmcnt(9)
	v_mfma_f32_16x16x32_bf16 v[188:191], v[92:95], v[8:11], v[64:67]
	v_mfma_f32_16x16x32_bf16 v[68:71], v[92:95], v[16:19], v[68:71]
	v_mfma_f32_16x16x32_bf16 v[92:95], v[76:79], v[12:15], v[162:165]
	v_mfma_f32_16x16x32_bf16 v[76:79], v[76:79], v[20:23], v[72:75]
	v_mfma_f32_16x16x32_bf16 v[88:91], v[84:87], v[12:15], v[166:169]
	v_mfma_f32_16x16x32_bf16 v[72:75], v[84:87], v[20:23], v[80:83]
	v_mfma_f32_16x16x32_bf16 v[84:87], v[154:157], v[12:15], v[180:183]
	v_mfma_f32_16x16x32_bf16 v[64:67], v[154:157], v[20:23], v[184:187]
	s_waitcnt lgkmcnt(8)
	v_mfma_f32_16x16x32_bf16 v[80:83], v[158:161], v[12:15], v[188:191]
	v_mfma_f32_16x16x32_bf16 v[68:71], v[158:161], v[20:23], v[68:71]
	s_waitcnt lgkmcnt(7)
	ds_read_b64_tr_b16 v[248:249], v228 offset:64
	ds_read_b64_tr_b16 v[250:251], v228 offset:2368
	ds_read_b64_tr_b16 v[198:199], v228 offset:4672
	ds_read_b64_tr_b16 v[200:201], v228 offset:6976
	ds_read_b64_tr_b16 v[202:203], v228 offset:96
	ds_read_b64_tr_b16 v[204:205], v228 offset:2400
	ds_read_b64_tr_b16 v[206:207], v228 offset:4704
	ds_read_b64_tr_b16 v[208:209], v228 offset:7008
	s_cbranch_vccnz .LBB0_271
	s_mov_b64 s[6:7], 0

; #define LAS __attribute__((address_space(3)))
; #define OPQV(x) asm volatile("" : "+v"(x))
; DEV void kv_store(LAS unsigned char* lds, const KVRegs& r, int buf, int tid) {
;     const int key = tid >> 3, c8 = (tid & 7) * 8;
;     unsigned kw = AT_KS + buf * 9216 + (key * 72 + c8) * 2, vw = AT_VT + buf * 9216 + ((tid >> 6) * 8 * 72 + (tid & 63)) * 2; OPQV(kw); OPQV(vw);
;     *(LAS u32x4*)(lds + kw) = r.k;
; #pragma unroll
;     for (int j = 0; j < 4; ++j) { *(LAS bf16_t*)(lds + vw + j * 288) = (bf16_t)(r.v[j] & 0xffffu); *(LAS bf16_t*)(lds + vw + j * 288 + 144) = (bf16_t)(r.v[j] >> 16); }
; }
; DEV void attn_item(LAS unsigned char* lds, const bf16_t* P, const bf16_t* QB, const bf16_t* KV, const bf16_t* KC, const bf16_t* VC, const float* rel_bias, bf16_t* OB, int b, int g, int qt) {
;     ...
;             kv_store(lds, pre, buf, tid);
;             __syncthreads();
.Lst_zz:
	s_min_u32 s100, s100, 1
	s_andn2_b64 vcc, exec, s[92:93]
	s_cbranch_vccz .Lst_exit
	s_xor_b32 s98, s98, 0x2400
	v_add_u32_e32 v228, s98, v139
	v_add_u32_e32 v229, s98, v194
	s_waitcnt vmcnt(1)
	ds_write_b128 v228, v[24:27]
	s_waitcnt vmcnt(0)
	ds_write_b128 v229, v[28:31]
	s_waitcnt lgkmcnt(0)
	s_barrier
	s_mov_b32 s97, s96
	s_mov_b32 s50, s52
	s_branch .LBB0_260

; #define LAS __attribute__((address_space(3)))
; DEV void attn_tile(LAS unsigned char* lds, const bf16x8 (&qf)[2][2], int tl, int kpos0, int mode, bool near, bool rowsel, const float (&cbias)[2],
;                    unsigned kb, unsigned vb_, unsigned btb, int g4, float (&mrun)[2], float (&lrun)[2], f32x4 (&O)[2][4]) {
;     ...
;     for (int dt = 0; dt < 4; ++dt)
; #pragma unroll
;         for (int kc = 0; kc < 2; ++kc) {
;             const u32x2 va = *(const LAS u32x2*)(lds + vb_ + dt * 2304 + kc * 64);
;             const u32x2 vb = *(const LAS u32x2*)(lds + vb_ + dt * 2304 + kc * 64 + 32);
;             const bf16x8 vf = as_bf16x8((u32x4){va.x, va.y, vb.x, vb.y});
; #pragma unroll
;             for (int hh = 0; hh < 2; ++hh) O[hh][dt] = __builtin_amdgcn_mfma_f32_16x16x32_bf16(vf, pf[hh][kc], O[hh][dt], 0, 0, 0);
;         }
; DEV void attn_item(LAS unsigned char* lds, const bf16_t* P, const bf16_t* QB, const bf16_t* KV, const bf16_t* KC, const bf16_t* VC, const float* rel_bias, bf16_t* OB, int b, int g, int qt) {
;     ...
;             if (mode_n != mode || !more) {
; #pragma unroll
;                 for (int hh = 0; hh < 2; ++hh) { float lt = lrun[hh]; lt += __shfl_xor(lt, 16); lt += __shfl_xor(lt, 32); const float sc = lt > 0.f ? gate[mode][hh] / lt : 0.f;
; #pragma unroll
;                     for (int dt = 0; dt < 4; ++dt) { F[hh][dt] = F[hh][dt] + O[hh][dt] * sc; O[hh][dt] = (f32x4){0.f, 0.f, 0.f, 0.f}; }
;                     mrun[hh] = NEG_; lrun[hh] = 0.f; }
.Lst_nokpre:
	s_waitcnt lgkmcnt(14)
	v_mfma_f32_16x16x32_bf16 v[44:47], v[232:235], v[162:165], v[44:47]
	v_mfma_f32_16x16x32_bf16 v[32:35], v[232:235], v[68:71], v[32:35]
	s_waitcnt lgkmcnt(12)
	v_mfma_f32_16x16x32_bf16 v[44:47], v[236:239], v[166:169], v[44:47]
	v_mfma_f32_16x16x32_bf16 v[32:35], v[236:239], v[64:67], v[32:35]
	s_waitcnt lgkmcnt(10)
	v_mfma_f32_16x16x32_bf16 v[56:59], v[240:243], v[162:165], v[56:59]
	v_mfma_f32_16x16x32_bf16 v[40:43], v[240:243], v[68:71], v[40:43]
	s_waitcnt lgkmcnt(8)
	v_mfma_f32_16x16x32_bf16 v[56:59], v[244:247], v[166:169], v[56:59]
	v_mfma_f32_16x16x32_bf16 v[40:43], v[244:247], v[64:67], v[40:43]
	s_waitcnt lgkmcnt(6)
	v_mfma_f32_16x16x32_bf16 v[52:55], v[248:251], v[162:165], v[52:55]
	v_mfma_f32_16x16x32_bf16 v[36:39], v[248:251], v[68:71], v[36:39]
	s_waitcnt lgkmcnt(4)
	v_mfma_f32_16x16x32_bf16 v[52:55], v[198:201], v[166:169], v[52:55]
	v_mfma_f32_16x16x32_bf16 v[36:39], v[198:201], v[64:67], v[36:39]
	s_waitcnt lgkmcnt(2)
	v_mfma_f32_16x16x32_bf16 v[48:51], v[202:205], v[68:71], v[48:51]
	v_mfma_f32_16x16x32_bf16 v[60:63], v[202:205], v[162:165], v[60:63]
	s_waitcnt lgkmcnt(0)
	v_mfma_f32_16x16x32_bf16 v[60:63], v[206:209], v[166:169], v[60:63]
	v_mfma_f32_16x16x32_bf16 v[48:51], v[206:209], v[64:67], v[48:51]
	s_bitcmp1_b32 s101, 8
	s_cbranch_scc0 .LBB0_283
	ds_bpermute_b32 v64, v143, v151
	s_and_b32 s6, s101, 0xff
	s_lshl_b32 s6, s6, 1
	v_mov_b32_e32 v66, 0
	s_waitcnt lgkmcnt(0)
	v_add_f32_e32 v64, v151, v64
	ds_bpermute_b32 v65, v144, v64
	s_waitcnt lgkmcnt(0)
	v_add_f32_e32 v65, v64, v65
	v_mov_b32_e32 v64, 0
	v_cmp_lt_f32_e32 vcc, 0, v65
	s_and_saveexec_b64 s[4:5], vcc
	s_cbranch_execz .LBB0_280
	s_cmp_eq_u32 s6, 1
	s_cselect_b64 vcc, -1, 0
	s_cmp_eq_u32 s6, 2
	v_cndmask_b32_e32 v66, v126, v7, vcc
	s_cselect_b64 vcc, -1, 0
	s_cmp_eq_u32 s6, 3
	v_cndmask_b32_e32 v66, v66, v2, vcc
	s_cselect_b64 vcc, -1, 0
	s_cmp_eq_u32 s6, 4
	v_cndmask_b32_e32 v66, v66, v3, vcc
	s_cselect_b64 vcc, -1, 0
	s_cmp_eq_u32 s6, 5
	v_cndmask_b32_e32 v66, v66, v4, vcc
	s_cselect_b64 vcc, -1, 0
	v_cndmask_b32_e32 v66, v66, v5, vcc
	v_div_scale_f32 v67, s[42:43], v65, v65, v66
	v_rcp_f32_e32 v68, v67
	s_nop 0
	v_fma_f32 v69, -v67, v68, 1.0
	v_fmac_f32_e32 v68, v69, v68
	v_div_scale_f32 v69, vcc, v66, v65, v66
	v_mul_f32_e32 v70, v69, v68
	v_fma_f32 v71, -v67, v70, v69
	v_fmac_f32_e32 v70, v71, v68
	v_fma_f32 v67, -v67, v70, v69
	v_div_fmas_f32 v67, v67, v68, v70
	v_div_fixup_f32 v66, v67, v65, v66
